# Epi3 main and second pass: flat loads/stores -> global with counted vmcnt waits (lgkmcnt waits no longer wait for global memory)
# speedup vs baseline: 1.0127x; 1.0029x over previous
.LBB0_675:
	s_or_b64 exec, exec, s[6:7]
	s_mov_b32 s0, 0x40000
	v_add_co_u32_e32 v156, vcc, s0, v202
	s_waitcnt lgkmcnt(0)
	s_waitcnt lgkmcnt(0)
	s_nop 0
	v_addc_co_u32_e32 v157, vcc, 0, v203, vcc
	s_barrier
	global_load_dwordx4 v[156:159], v[156:157], off
	v_lshl_add_u32 v3, v188, 2, 0
	v_add_u32_e32 v3, 0x22c00, v3
	ds_read_b32 v204, v3
	s_waitcnt vmcnt(1)
	v_lshlrev_b32_e32 v206, 16, v160
	v_and_b32_e32 v207, 0xffff0000, v160
	v_lshlrev_b32_e32 v160, 16, v161
	v_and_b32_e32 v161, 0xffff0000, v161
	s_waitcnt lgkmcnt(0)
	v_pk_mul_f32 v[130:131], v[130:131], v[204:205] op_sel_hi:[1,0]
	v_readlane_b32 s10, v252, 37
	v_lshlrev_b32_e32 v208, 16, v162
	v_and_b32_e32 v209, 0xffff0000, v162
	v_lshlrev_b32_e32 v162, 16, v163
	v_and_b32_e32 v163, 0xffff0000, v163
	v_pk_mul_f32 v[128:129], v[128:129], v[204:205] op_sel_hi:[1,0]
	v_pk_fma_f32 v[130:131], v[146:147], v[130:131], v[160:161]
	v_pk_mul_f32 v[124:125], v[124:125], v[204:205] op_sel_hi:[1,0]
	v_pk_mul_f32 v[126:127], v[126:127], v[204:205] op_sel_hi:[1,0]
	v_cndmask_b32_e64 v160, 0, 1, s[20:21]
	v_readlane_b32 s11, v252, 38
	v_pk_fma_f32 v[128:129], v[144:145], v[128:129], v[206:207]
	v_pk_fma_f32 v[126:127], v[142:143], v[126:127], v[162:163]
	v_pk_fma_f32 v[124:125], v[140:141], v[124:125], v[208:209]
	s_mov_b64 s[6:7], -1
	v_cmp_ne_u32_e64 s[0:1], 1, v160
	s_andn2_b64 vcc, exec, s[20:21]
	v_lshl_add_u64 v[208:209], v[194:195], 2, s[10:11]
	s_cbranch_vccnz .LBB0_677
	s_mov_b64 s[6:7], 0
	global_store_dwordx4 v[208:209], v[128:131], off
	global_store_dwordx4 v[208:209], v[124:127], off offset:16
.LBB0_677:
	s_andn2_b64 vcc, exec, s[6:7]
	v_lshl_add_u64 v[206:207], v[194:195], 1, s[34:35]
	s_cbranch_vccnz .LBB0_679
	v_cvt_pk_bf16_f32 v160, v128, v129
	v_cvt_pk_bf16_f32 v161, v130, v131
	v_cvt_pk_bf16_f32 v162, v124, v125
	v_cvt_pk_bf16_f32 v163, v126, v127
	global_store_dwordx4 v[206:207], v[160:163], off
.LBB0_679:
	s_nop 1
	v_add_co_u32_e32 v160, vcc, 0x40000, v202
	v_mov_b32_e32 v205, v204
	s_nop 0
	v_addc_co_u32_e32 v161, vcc, 0, v203, vcc
	global_load_dwordx4 v[160:163], v[160:161], off offset:256
	v_mov_b32_e32 v238, v204
	v_mov_b32_e32 v239, v204
	v_lshlrev_b32_e32 v202, 16, v168
	v_and_b32_e32 v203, 0xffff0000, v168
	v_lshlrev_b32_e32 v168, 16, v169
	v_and_b32_e32 v169, 0xffff0000, v169
	v_lshlrev_b32_e32 v236, 16, v170
	v_and_b32_e32 v237, 0xffff0000, v170
	v_lshlrev_b32_e32 v170, 16, v171
	v_and_b32_e32 v171, 0xffff0000, v171
	v_pk_mul_f32 v[98:99], v[98:99], v[238:239]
	v_pk_mul_f32 v[96:97], v[96:97], v[204:205]
	v_pk_mul_f32 v[94:95], v[94:95], v[238:239]
	v_pk_mul_f32 v[92:93], v[92:93], v[204:205]
	v_pk_fma_f32 v[98:99], v[138:139], v[98:99], v[168:169]
	v_pk_fma_f32 v[96:97], v[136:137], v[96:97], v[202:203]
	v_pk_fma_f32 v[94:95], v[134:135], v[94:95], v[170:171]
	v_pk_fma_f32 v[92:93], v[132:133], v[92:93], v[236:237]
	s_and_b64 vcc, exec, s[0:1]
	s_mov_b64 s[6:7], -1
	s_cbranch_vccnz .LBB0_682
	global_store_dwordx4 v[208:209], v[96:99], off offset:512
	global_store_dwordx4 v[208:209], v[92:95], off offset:528
	s_cbranch_execz .LBB0_683

.LBB0_683:
	v_cvt_pk_bf16_f32 v168, v96, v97
	v_cvt_pk_bf16_f32 v169, v98, v99
	v_cvt_pk_bf16_f32 v170, v92, v93
	v_cvt_pk_bf16_f32 v171, v94, v95
	global_store_dwordx4 v[206:207], v[168:171], off offset:256
	s_nop 1
	v_cndmask_b32_e64 v168, 0, 1, s[66:67]
	v_cmp_ne_u32_e64 s[6:7], 1, v168
	s_andn2_b64 vcc, exec, s[66:67]
	s_cbranch_vccnz .LBB0_687

.LBB0_687:
	s_mov_b32 s10, 0x40000
	v_add_co_u32_e32 v168, vcc, s10, v200
	ds_read_b32 v202, v3 offset:64
	s_waitcnt lgkmcnt(0)
	v_addc_co_u32_e32 v169, vcc, 0, v201, vcc
	global_load_dwordx4 v[168:171], v[168:169], off
	s_mov_b64 s[10:11], 0x4000
	v_readlane_b32 s38, v252, 37
	v_lshl_add_u64 v[204:205], v[194:195], 0, s[10:11]
	v_lshlrev_b32_e32 v206, 16, v172
	v_and_b32_e32 v207, 0xffff0000, v172
	v_lshlrev_b32_e32 v172, 16, v173
	v_and_b32_e32 v173, 0xffff0000, v173
	v_lshlrev_b32_e32 v208, 16, v174
	v_and_b32_e32 v209, 0xffff0000, v174
	v_lshlrev_b32_e32 v174, 16, v175
	v_and_b32_e32 v175, 0xffff0000, v175
	v_pk_mul_f32 v[122:123], v[122:123], v[202:203] op_sel_hi:[1,0]
	v_pk_mul_f32 v[120:121], v[120:121], v[202:203] op_sel_hi:[1,0]
	v_pk_mul_f32 v[118:119], v[118:119], v[202:203] op_sel_hi:[1,0]
	v_pk_mul_f32 v[116:117], v[116:117], v[202:203] op_sel_hi:[1,0]
	v_readlane_b32 s39, v252, 38
	v_pk_fma_f32 v[122:123], v[146:147], v[122:123], v[172:173]
	v_pk_fma_f32 v[120:121], v[144:145], v[120:121], v[206:207]
	v_pk_fma_f32 v[118:119], v[142:143], v[118:119], v[174:175]
	v_pk_fma_f32 v[116:117], v[140:141], v[116:117], v[208:209]
	s_mov_b64 s[10:11], -1
	s_and_b64 vcc, exec, s[0:1]
	v_lshl_add_u64 v[206:207], v[204:205], 2, s[38:39]
	s_cbranch_vccnz .LBB0_689
	s_mov_b64 s[10:11], 0
	global_store_dwordx4 v[206:207], v[120:123], off
	global_store_dwordx4 v[206:207], v[116:119], off offset:16
.LBB0_689:
	s_andn2_b64 vcc, exec, s[10:11]
	v_lshl_add_u64 v[204:205], v[204:205], 1, s[34:35]
	s_cbranch_vccnz .LBB0_691
	v_cvt_pk_bf16_f32 v172, v120, v121
	v_cvt_pk_bf16_f32 v173, v122, v123
	v_cvt_pk_bf16_f32 v174, v116, v117
	v_cvt_pk_bf16_f32 v175, v118, v119
	global_store_dwordx4 v[204:205], v[172:175], off
.LBB0_691:
	s_nop 1
	v_add_co_u32_e32 v172, vcc, 0x40000, v200
	v_mov_b32_e32 v203, v202
	s_nop 0
	v_addc_co_u32_e32 v173, vcc, 0, v201, vcc
	global_load_dwordx4 v[172:175], v[172:173], off offset:256
	v_mov_b32_e32 v236, v202
	v_mov_b32_e32 v237, v202
	v_lshlrev_b32_e32 v200, 16, v176
	v_and_b32_e32 v201, 0xffff0000, v176
	v_lshlrev_b32_e32 v176, 16, v177
	v_and_b32_e32 v177, 0xffff0000, v177
	v_lshlrev_b32_e32 v208, 16, v178
	v_and_b32_e32 v209, 0xffff0000, v178
	v_lshlrev_b32_e32 v178, 16, v179
	v_and_b32_e32 v179, 0xffff0000, v179
	v_pk_mul_f32 v[90:91], v[90:91], v[236:237]
	v_pk_mul_f32 v[88:89], v[88:89], v[202:203]
	v_pk_mul_f32 v[86:87], v[86:87], v[236:237]
	v_pk_mul_f32 v[84:85], v[84:85], v[202:203]
	v_pk_fma_f32 v[90:91], v[138:139], v[90:91], v[176:177]
	v_pk_fma_f32 v[88:89], v[136:137], v[88:89], v[200:201]
	v_pk_fma_f32 v[86:87], v[134:135], v[86:87], v[178:179]
	v_pk_fma_f32 v[84:85], v[132:133], v[84:85], v[208:209]
	s_and_b64 vcc, exec, s[0:1]
	s_mov_b64 s[84:85], -1
	s_cbranch_vccnz .LBB0_694
	global_store_dwordx4 v[206:207], v[88:91], off offset:512
	global_store_dwordx4 v[206:207], v[84:87], off offset:528
	s_cbranch_execz .LBB0_695

.LBB0_695:
	v_cvt_pk_bf16_f32 v176, v88, v89
	v_cvt_pk_bf16_f32 v177, v90, v91
	v_cvt_pk_bf16_f32 v178, v84, v85
	v_cvt_pk_bf16_f32 v179, v86, v87
	global_store_dwordx4 v[204:205], v[176:179], off offset:256
	s_and_b64 vcc, exec, s[6:7]
	v_add_u32_e32 v189, 16, v188
	s_cbranch_vccnz .LBB0_699

.LBB0_699:
	v_add_co_u32_e32 v176, vcc, 0x40000, v198
	ds_read_b32 v200, v3 offset:128
	s_waitcnt lgkmcnt(0)
	v_addc_co_u32_e32 v177, vcc, 0, v199, vcc
	global_load_dwordx4 v[176:179], v[176:177], off
	s_mov_b64 s[10:11], 0x8000
	v_readlane_b32 s38, v252, 37
	v_lshl_add_u64 v[202:203], v[194:195], 0, s[10:11]
	v_lshlrev_b32_e32 v204, 16, v180
	v_and_b32_e32 v205, 0xffff0000, v180
	v_lshlrev_b32_e32 v180, 16, v181
	v_and_b32_e32 v181, 0xffff0000, v181
	v_lshlrev_b32_e32 v206, 16, v182
	v_and_b32_e32 v207, 0xffff0000, v182
	v_lshlrev_b32_e32 v182, 16, v183
	v_and_b32_e32 v183, 0xffff0000, v183
	v_pk_mul_f32 v[114:115], v[114:115], v[200:201] op_sel_hi:[1,0]
	v_pk_mul_f32 v[112:113], v[112:113], v[200:201] op_sel_hi:[1,0]
	v_pk_mul_f32 v[110:111], v[110:111], v[200:201] op_sel_hi:[1,0]
	v_pk_mul_f32 v[108:109], v[108:109], v[200:201] op_sel_hi:[1,0]
	v_readlane_b32 s39, v252, 38
	v_pk_fma_f32 v[114:115], v[146:147], v[114:115], v[180:181]
	v_pk_fma_f32 v[112:113], v[144:145], v[112:113], v[204:205]
	v_pk_fma_f32 v[110:111], v[142:143], v[110:111], v[182:183]
	v_pk_fma_f32 v[108:109], v[140:141], v[108:109], v[206:207]
	s_mov_b64 s[10:11], -1
	s_and_b64 vcc, exec, s[0:1]
	v_lshl_add_u64 v[204:205], v[202:203], 2, s[38:39]
	s_cbranch_vccnz .LBB0_701
	s_mov_b64 s[10:11], 0
	global_store_dwordx4 v[204:205], v[112:115], off
	global_store_dwordx4 v[204:205], v[108:111], off offset:16
.LBB0_701:
	s_andn2_b64 vcc, exec, s[10:11]
	v_lshl_add_u64 v[202:203], v[202:203], 1, s[34:35]
	s_cbranch_vccnz .LBB0_703
	v_cvt_pk_bf16_f32 v180, v112, v113
	v_cvt_pk_bf16_f32 v181, v114, v115
	v_cvt_pk_bf16_f32 v182, v108, v109
	v_cvt_pk_bf16_f32 v183, v110, v111
	global_store_dwordx4 v[202:203], v[180:183], off
.LBB0_703:
	s_nop 1
	v_add_co_u32_e32 v180, vcc, 0x40000, v198
	v_mov_b32_e32 v201, v200
	s_nop 0
	v_addc_co_u32_e32 v181, vcc, 0, v199, vcc
	global_load_dwordx4 v[180:183], v[180:181], off offset:256
	v_mov_b32_e32 v208, v200
	v_mov_b32_e32 v209, v200
	v_lshlrev_b32_e32 v198, 16, v164
	v_and_b32_e32 v199, 0xffff0000, v164
	v_lshlrev_b32_e32 v164, 16, v165
	v_and_b32_e32 v165, 0xffff0000, v165
	v_lshlrev_b32_e32 v206, 16, v166
	v_and_b32_e32 v207, 0xffff0000, v166
	v_lshlrev_b32_e32 v166, 16, v167
	v_and_b32_e32 v167, 0xffff0000, v167
	v_pk_mul_f32 v[82:83], v[82:83], v[208:209]
	v_pk_mul_f32 v[80:81], v[80:81], v[200:201]
	v_pk_mul_f32 v[78:79], v[78:79], v[208:209]
	v_pk_mul_f32 v[76:77], v[76:77], v[200:201]
	v_pk_fma_f32 v[82:83], v[138:139], v[82:83], v[164:165]
	v_pk_fma_f32 v[80:81], v[136:137], v[80:81], v[198:199]
	v_pk_fma_f32 v[78:79], v[134:135], v[78:79], v[166:167]
	v_pk_fma_f32 v[76:77], v[132:133], v[76:77], v[206:207]
	s_and_b64 vcc, exec, s[0:1]
	s_mov_b64 s[84:85], -1
	s_cbranch_vccnz .LBB0_706
	global_store_dwordx4 v[204:205], v[80:83], off offset:512
	global_store_dwordx4 v[204:205], v[76:79], off offset:528
	s_cbranch_execz .LBB0_707

.LBB0_707:
	v_cvt_pk_bf16_f32 v164, v80, v81
	v_cvt_pk_bf16_f32 v165, v82, v83
	v_cvt_pk_bf16_f32 v166, v76, v77
	v_cvt_pk_bf16_f32 v167, v78, v79
	global_store_dwordx4 v[202:203], v[164:167], off offset:256
	s_and_b64 vcc, exec, s[6:7]
	v_add_u32_e32 v204, 32, v188
	s_cbranch_vccnz .LBB0_711

.LBB0_711:
	v_add_co_u32_e32 v164, vcc, 0x40000, v196
	ds_read_b32 v198, v3 offset:192
	s_waitcnt lgkmcnt(0)
	v_addc_co_u32_e32 v165, vcc, 0, v197, vcc
	global_load_dwordx4 v[164:167], v[164:165], off
	s_mov_b64 s[10:11], 0xc000
	v_readlane_b32 s38, v252, 37
	v_lshl_add_u64 v[200:201], v[194:195], 0, s[10:11]
	v_lshlrev_b32_e32 v202, 16, v152
	v_and_b32_e32 v203, 0xffff0000, v152
	v_lshlrev_b32_e32 v152, 16, v153
	v_and_b32_e32 v153, 0xffff0000, v153
	v_lshlrev_b32_e32 v206, 16, v154
	v_and_b32_e32 v207, 0xffff0000, v154
	v_lshlrev_b32_e32 v154, 16, v155
	v_and_b32_e32 v155, 0xffff0000, v155
	v_pk_mul_f32 v[106:107], v[106:107], v[198:199] op_sel_hi:[1,0]
	v_pk_mul_f32 v[104:105], v[104:105], v[198:199] op_sel_hi:[1,0]
	v_pk_mul_f32 v[102:103], v[102:103], v[198:199] op_sel_hi:[1,0]
	v_pk_mul_f32 v[100:101], v[100:101], v[198:199] op_sel_hi:[1,0]
	v_readlane_b32 s39, v252, 38
	v_pk_fma_f32 v[106:107], v[146:147], v[106:107], v[152:153]
	v_pk_fma_f32 v[104:105], v[144:145], v[104:105], v[202:203]
	v_pk_fma_f32 v[102:103], v[142:143], v[102:103], v[154:155]
	v_pk_fma_f32 v[100:101], v[140:141], v[100:101], v[206:207]
	s_mov_b64 s[10:11], -1
	s_and_b64 vcc, exec, s[0:1]
	v_lshl_add_u64 v[202:203], v[200:201], 2, s[38:39]
	s_cbranch_vccnz .LBB0_713
	s_mov_b64 s[10:11], 0
	global_store_dwordx4 v[202:203], v[104:107], off
	global_store_dwordx4 v[202:203], v[100:103], off offset:16
.LBB0_713:
	s_andn2_b64 vcc, exec, s[10:11]
	v_lshl_add_u64 v[200:201], v[200:201], 1, s[34:35]
	s_cbranch_vccnz .LBB0_715
	v_cvt_pk_bf16_f32 v152, v104, v105
	v_cvt_pk_bf16_f32 v153, v106, v107
	v_cvt_pk_bf16_f32 v154, v100, v101
	v_cvt_pk_bf16_f32 v155, v102, v103
	global_store_dwordx4 v[200:201], v[152:155], off
.LBB0_715:
	s_nop 1
	v_add_co_u32_e32 v152, vcc, 0x40000, v196
	v_mov_b32_e32 v199, v198
	s_nop 0
	v_addc_co_u32_e32 v153, vcc, 0, v197, vcc
	global_load_dwordx4 v[152:155], v[152:153], off offset:256
	v_mov_b32_e32 v208, v198
	v_mov_b32_e32 v209, v198
	v_lshlrev_b32_e32 v196, 16, v148
	v_and_b32_e32 v197, 0xffff0000, v148
	v_lshlrev_b32_e32 v148, 16, v149
	v_and_b32_e32 v149, 0xffff0000, v149
	v_lshlrev_b32_e32 v206, 16, v150
	v_and_b32_e32 v207, 0xffff0000, v150
	v_lshlrev_b32_e32 v150, 16, v151
	v_and_b32_e32 v151, 0xffff0000, v151
	v_pk_mul_f32 v[74:75], v[74:75], v[208:209]
	v_pk_mul_f32 v[72:73], v[72:73], v[198:199]
	v_pk_mul_f32 v[70:71], v[70:71], v[208:209]
	v_pk_mul_f32 v[68:69], v[68:69], v[198:199]
	v_pk_fma_f32 v[74:75], v[138:139], v[74:75], v[148:149]
	v_pk_fma_f32 v[72:73], v[136:137], v[72:73], v[196:197]
	v_pk_fma_f32 v[70:71], v[134:135], v[70:71], v[150:151]
	v_pk_fma_f32 v[68:69], v[132:133], v[68:69], v[206:207]
	s_and_b64 vcc, exec, s[0:1]
	s_mov_b64 s[84:85], -1
	s_cbranch_vccnz .LBB0_718
	global_store_dwordx4 v[202:203], v[72:75], off offset:512
	global_store_dwordx4 v[202:203], v[68:71], off offset:528
	s_cbranch_execz .LBB0_719

.LBB0_719:
	v_cvt_pk_bf16_f32 v148, v72, v73
	v_cvt_pk_bf16_f32 v149, v74, v75
	v_cvt_pk_bf16_f32 v150, v68, v69
	v_cvt_pk_bf16_f32 v151, v70, v71
	global_store_dwordx4 v[200:201], v[148:151], off offset:256
	s_and_b64 vcc, exec, s[6:7]
	v_add_u32_e32 v196, 48, v188
	s_cbranch_vccnz .LBB0_723

.LBB0_723:
	ds_read_b32 v148, v3 offset:512
	s_mov_b64 s[10:11], 0x20000
	v_readlane_b32 s38, v252, 37
	v_lshl_add_u64 v[150:151], v[194:195], 0, s[10:11]
	s_waitcnt vmcnt(15)
	v_lshlrev_b32_e32 v198, 16, v158
	v_and_b32_e32 v199, 0xffff0000, v158
	v_lshlrev_b32_e32 v158, 16, v159
	v_and_b32_e32 v159, 0xffff0000, v159
	v_lshlrev_b32_e32 v200, 16, v156
	v_and_b32_e32 v201, 0xffff0000, v156
	v_lshlrev_b32_e32 v156, 16, v157
	v_and_b32_e32 v157, 0xffff0000, v157
	s_waitcnt lgkmcnt(0)
	v_pk_mul_f32 v[66:67], v[66:67], v[148:149] op_sel_hi:[1,0]
	v_pk_mul_f32 v[64:65], v[64:65], v[148:149] op_sel_hi:[1,0]
	v_pk_mul_f32 v[62:63], v[62:63], v[148:149] op_sel_hi:[1,0]
	v_pk_mul_f32 v[60:61], v[60:61], v[148:149] op_sel_hi:[1,0]
	v_readlane_b32 s39, v252, 38
	v_pk_fma_f32 v[66:67], v[146:147], v[66:67], v[156:157]
	v_pk_fma_f32 v[64:65], v[144:145], v[64:65], v[200:201]
	v_pk_fma_f32 v[62:63], v[142:143], v[62:63], v[158:159]
	v_pk_fma_f32 v[60:61], v[140:141], v[60:61], v[198:199]
	s_mov_b64 s[10:11], -1
	s_and_b64 vcc, exec, s[0:1]
	v_lshl_add_u64 v[156:157], v[150:151], 2, s[38:39]
	s_cbranch_vccnz .LBB0_725
	s_mov_b64 s[10:11], 0
	global_store_dwordx4 v[156:157], v[64:67], off
	global_store_dwordx4 v[156:157], v[60:63], off offset:16
.LBB0_725:
	s_andn2_b64 vcc, exec, s[10:11]
	v_lshl_add_u64 v[150:151], v[150:151], 1, s[34:35]
	s_cbranch_vccnz .LBB0_727
	v_cvt_pk_bf16_f32 v198, v64, v65
	v_cvt_pk_bf16_f32 v199, v66, v67
	v_cvt_pk_bf16_f32 v200, v60, v61
	v_cvt_pk_bf16_f32 v201, v62, v63
	global_store_dwordx4 v[150:151], v[198:201], off
.LBB0_727:
	v_mov_b32_e32 v149, v148
	s_nop 0
	v_mov_b32_e32 v200, v148
	v_mov_b32_e32 v201, v148
	s_waitcnt vmcnt(14)
	v_lshlrev_b32_e32 v158, 16, v162
	v_and_b32_e32 v159, 0xffff0000, v162
	v_lshlrev_b32_e32 v162, 16, v163
	v_and_b32_e32 v163, 0xffff0000, v163
	v_lshlrev_b32_e32 v198, 16, v160
	v_and_b32_e32 v199, 0xffff0000, v160
	v_lshlrev_b32_e32 v160, 16, v161
	v_and_b32_e32 v161, 0xffff0000, v161
	v_pk_mul_f32 v[34:35], v[34:35], v[200:201]
	v_pk_mul_f32 v[32:33], v[32:33], v[148:149]
	v_pk_mul_f32 v[30:31], v[30:31], v[200:201]
	v_pk_mul_f32 v[28:29], v[28:29], v[148:149]
	v_pk_fma_f32 v[34:35], v[138:139], v[34:35], v[160:161]
	v_pk_fma_f32 v[32:33], v[136:137], v[32:33], v[198:199]
	v_pk_fma_f32 v[30:31], v[134:135], v[30:31], v[162:163]
	v_pk_fma_f32 v[28:29], v[132:133], v[28:29], v[158:159]
	s_and_b64 vcc, exec, s[0:1]
	s_mov_b64 s[84:85], -1
	s_cbranch_vccnz .LBB0_730
	global_store_dwordx4 v[156:157], v[32:35], off offset:512
	global_store_dwordx4 v[156:157], v[28:31], off offset:528
	s_cbranch_execz .LBB0_731

.LBB0_731:
	v_cvt_pk_bf16_f32 v156, v32, v33
	v_cvt_pk_bf16_f32 v157, v34, v35
	v_cvt_pk_bf16_f32 v158, v28, v29
	v_cvt_pk_bf16_f32 v159, v30, v31
	global_store_dwordx4 v[150:151], v[156:159], off offset:256
	s_and_b64 vcc, exec, s[6:7]
	s_nop 0
	v_add_u32_e32 v158, 0x80, v188
	s_cbranch_vccnz .LBB0_735

.LBB0_735:
	ds_read_b32 v148, v3 offset:576
	s_mov_b64 s[10:11], 0x24000
	v_readlane_b32 s38, v252, 37
	v_lshl_add_u64 v[150:151], v[194:195], 0, s[10:11]
	s_waitcnt vmcnt(13)
	v_lshlrev_b32_e32 v156, 16, v170
	v_and_b32_e32 v157, 0xffff0000, v170
	v_lshlrev_b32_e32 v160, 16, v171
	v_and_b32_e32 v161, 0xffff0000, v171
	v_lshlrev_b32_e32 v162, 16, v168
	v_and_b32_e32 v163, 0xffff0000, v168
	v_lshlrev_b32_e32 v168, 16, v169
	v_and_b32_e32 v169, 0xffff0000, v169
	s_waitcnt lgkmcnt(0)
	v_pk_mul_f32 v[58:59], v[58:59], v[148:149] op_sel_hi:[1,0]
	v_pk_mul_f32 v[56:57], v[56:57], v[148:149] op_sel_hi:[1,0]
	v_pk_mul_f32 v[54:55], v[54:55], v[148:149] op_sel_hi:[1,0]
	v_pk_mul_f32 v[52:53], v[52:53], v[148:149] op_sel_hi:[1,0]
	v_readlane_b32 s39, v252, 38
	v_pk_fma_f32 v[58:59], v[146:147], v[58:59], v[168:169]
	v_pk_fma_f32 v[56:57], v[144:145], v[56:57], v[162:163]
	v_pk_fma_f32 v[54:55], v[142:143], v[54:55], v[160:161]
	v_pk_fma_f32 v[52:53], v[140:141], v[52:53], v[156:157]
	s_mov_b64 s[10:11], -1
	s_and_b64 vcc, exec, s[0:1]
	v_lshl_add_u64 v[156:157], v[150:151], 2, s[38:39]
	s_cbranch_vccnz .LBB0_737
	s_mov_b64 s[10:11], 0
	global_store_dwordx4 v[156:157], v[56:59], off
	global_store_dwordx4 v[156:157], v[52:55], off offset:16
.LBB0_737:
	s_andn2_b64 vcc, exec, s[10:11]
	v_lshl_add_u64 v[150:151], v[150:151], 1, s[34:35]
	s_cbranch_vccnz .LBB0_739
	v_cvt_pk_bf16_f32 v160, v56, v57
	v_cvt_pk_bf16_f32 v161, v58, v59
	v_cvt_pk_bf16_f32 v162, v52, v53
	v_cvt_pk_bf16_f32 v163, v54, v55
	global_store_dwordx4 v[150:151], v[160:163], off
.LBB0_739:
	v_mov_b32_e32 v149, v148
	s_waitcnt vmcnt(12)
	v_lshlrev_b32_e32 v168, 16, v172
	v_and_b32_e32 v169, 0xffff0000, v172
	v_lshlrev_b32_e32 v170, 16, v173
	v_and_b32_e32 v171, 0xffff0000, v173
	v_mov_b32_e32 v172, v148
	v_mov_b32_e32 v173, v148
	v_lshlrev_b32_e32 v160, 16, v174
	v_and_b32_e32 v161, 0xffff0000, v174
	v_lshlrev_b32_e32 v162, 16, v175
	v_and_b32_e32 v163, 0xffff0000, v175
	v_pk_mul_f32 v[26:27], v[26:27], v[172:173]
	v_pk_mul_f32 v[24:25], v[24:25], v[148:149]
	v_pk_mul_f32 v[22:23], v[22:23], v[172:173]
	v_pk_mul_f32 v[20:21], v[20:21], v[148:149]
	v_pk_fma_f32 v[26:27], v[138:139], v[26:27], v[170:171]
	v_pk_fma_f32 v[24:25], v[136:137], v[24:25], v[168:169]
	v_pk_fma_f32 v[22:23], v[134:135], v[22:23], v[162:163]
	v_pk_fma_f32 v[20:21], v[132:133], v[20:21], v[160:161]
	s_and_b64 vcc, exec, s[0:1]
	s_mov_b64 s[84:85], -1
	s_cbranch_vccnz .LBB0_742
	global_store_dwordx4 v[156:157], v[24:27], off offset:512
	global_store_dwordx4 v[156:157], v[20:23], off offset:528
	s_cbranch_execz .LBB0_743

.LBB0_743:
	v_cvt_pk_bf16_f32 v160, v24, v25
	v_cvt_pk_bf16_f32 v161, v26, v27
	v_cvt_pk_bf16_f32 v162, v20, v21
	v_cvt_pk_bf16_f32 v163, v22, v23
	global_store_dwordx4 v[150:151], v[160:163], off offset:256
	s_and_b64 vcc, exec, s[6:7]
	v_add_u32_e32 v159, 0x90, v188
	s_cbranch_vccnz .LBB0_747

.LBB0_747:
	ds_read_b32 v148, v3 offset:640
	s_mov_b64 s[10:11], 0x28000
	v_readlane_b32 s38, v252, 37
	v_lshl_add_u64 v[150:151], v[194:195], 0, s[10:11]
	s_waitcnt vmcnt(11)
	v_lshlrev_b32_e32 v156, 16, v178
	v_and_b32_e32 v157, 0xffff0000, v178
	v_lshlrev_b32_e32 v160, 16, v179
	v_and_b32_e32 v161, 0xffff0000, v179
	v_lshlrev_b32_e32 v162, 16, v176
	v_and_b32_e32 v163, 0xffff0000, v176
	v_lshlrev_b32_e32 v168, 16, v177
	v_and_b32_e32 v169, 0xffff0000, v177
	s_waitcnt lgkmcnt(0)
	v_pk_mul_f32 v[50:51], v[50:51], v[148:149] op_sel_hi:[1,0]
	v_pk_mul_f32 v[48:49], v[48:49], v[148:149] op_sel_hi:[1,0]
	v_pk_mul_f32 v[46:47], v[46:47], v[148:149] op_sel_hi:[1,0]
	v_pk_mul_f32 v[44:45], v[44:45], v[148:149] op_sel_hi:[1,0]
	v_readlane_b32 s39, v252, 38
	v_pk_fma_f32 v[50:51], v[146:147], v[50:51], v[168:169]
	v_pk_fma_f32 v[48:49], v[144:145], v[48:49], v[162:163]
	v_pk_fma_f32 v[46:47], v[142:143], v[46:47], v[160:161]
	v_pk_fma_f32 v[44:45], v[140:141], v[44:45], v[156:157]
	s_mov_b64 s[10:11], -1
	s_and_b64 vcc, exec, s[0:1]
	v_lshl_add_u64 v[156:157], v[150:151], 2, s[38:39]
	s_cbranch_vccnz .LBB0_749
	s_mov_b64 s[10:11], 0
	global_store_dwordx4 v[156:157], v[48:51], off
	global_store_dwordx4 v[156:157], v[44:47], off offset:16
.LBB0_749:
	s_andn2_b64 vcc, exec, s[10:11]
	v_lshl_add_u64 v[150:151], v[150:151], 1, s[34:35]
	s_cbranch_vccnz .LBB0_751
	v_cvt_pk_bf16_f32 v160, v48, v49
	v_cvt_pk_bf16_f32 v161, v50, v51
	v_cvt_pk_bf16_f32 v162, v44, v45
	v_cvt_pk_bf16_f32 v163, v46, v47
	global_store_dwordx4 v[150:151], v[160:163], off
.LBB0_751:
	v_mov_b32_e32 v149, v148
	v_mov_b32_e32 v172, v148
	v_mov_b32_e32 v173, v148
	s_waitcnt vmcnt(10)
	v_lshlrev_b32_e32 v160, 16, v182
	v_and_b32_e32 v161, 0xffff0000, v182
	v_lshlrev_b32_e32 v162, 16, v183
	v_and_b32_e32 v163, 0xffff0000, v183
	v_lshlrev_b32_e32 v168, 16, v180
	v_and_b32_e32 v169, 0xffff0000, v180
	v_lshlrev_b32_e32 v170, 16, v181
	v_and_b32_e32 v171, 0xffff0000, v181
	v_pk_mul_f32 v[18:19], v[18:19], v[172:173]
	v_pk_mul_f32 v[16:17], v[16:17], v[148:149]
	v_pk_mul_f32 v[14:15], v[14:15], v[172:173]
	v_pk_mul_f32 v[12:13], v[12:13], v[148:149]
	v_pk_fma_f32 v[18:19], v[138:139], v[18:19], v[170:171]
	v_pk_fma_f32 v[16:17], v[136:137], v[16:17], v[168:169]
	v_pk_fma_f32 v[14:15], v[134:135], v[14:15], v[162:163]
	v_pk_fma_f32 v[12:13], v[132:133], v[12:13], v[160:161]
	s_and_b64 vcc, exec, s[0:1]
	s_mov_b64 s[84:85], -1
	s_cbranch_vccnz .LBB0_754
	global_store_dwordx4 v[156:157], v[16:19], off offset:512
	global_store_dwordx4 v[156:157], v[12:15], off offset:528
	s_cbranch_execz .LBB0_755

.LBB0_755:
	v_cvt_pk_bf16_f32 v160, v16, v17
	v_cvt_pk_bf16_f32 v161, v18, v19
	v_cvt_pk_bf16_f32 v162, v12, v13
	v_cvt_pk_bf16_f32 v163, v14, v15
	global_store_dwordx4 v[150:151], v[160:163], off offset:256
	s_and_b64 vcc, exec, s[6:7]
	v_add_u32_e32 v156, 0xa0, v188
	s_cbranch_vccnz .LBB0_759

.LBB0_759:
	ds_read_b32 v148, v3 offset:704
	s_mov_b64 s[10:11], 0x2c000
	v_readlane_b32 s38, v252, 37
	v_lshl_add_u64 v[150:151], v[194:195], 0, s[10:11]
	s_waitcnt vmcnt(9)
	v_lshlrev_b32_e32 v160, 16, v166
	v_and_b32_e32 v161, 0xffff0000, v166
	v_lshlrev_b32_e32 v162, 16, v167
	v_and_b32_e32 v163, 0xffff0000, v167
	v_lshlrev_b32_e32 v166, 16, v164
	v_and_b32_e32 v167, 0xffff0000, v164
	v_lshlrev_b32_e32 v164, 16, v165
	v_and_b32_e32 v165, 0xffff0000, v165
	s_waitcnt lgkmcnt(0)
	v_pk_mul_f32 v[42:43], v[42:43], v[148:149] op_sel_hi:[1,0]
	v_pk_mul_f32 v[40:41], v[40:41], v[148:149] op_sel_hi:[1,0]
	v_pk_mul_f32 v[38:39], v[38:39], v[148:149] op_sel_hi:[1,0]
	v_pk_mul_f32 v[36:37], v[36:37], v[148:149] op_sel_hi:[1,0]
	v_readlane_b32 s39, v252, 38
	v_pk_fma_f32 v[42:43], v[146:147], v[42:43], v[164:165]
	v_pk_fma_f32 v[40:41], v[144:145], v[40:41], v[166:167]
	v_pk_fma_f32 v[38:39], v[142:143], v[38:39], v[162:163]
	v_pk_fma_f32 v[36:37], v[140:141], v[36:37], v[160:161]
	s_mov_b64 s[10:11], -1
	s_and_b64 vcc, exec, s[0:1]
	v_lshl_add_u64 v[142:143], v[150:151], 2, s[38:39]
	s_cbranch_vccnz .LBB0_761
	s_mov_b64 s[10:11], 0
	global_store_dwordx4 v[142:143], v[40:43], off
	global_store_dwordx4 v[142:143], v[36:39], off offset:16
.LBB0_761:
	s_andn2_b64 vcc, exec, s[10:11]
	v_lshl_add_u64 v[140:141], v[150:151], 1, s[34:35]
	s_cbranch_vccnz .LBB0_763
	v_cvt_pk_bf16_f32 v144, v40, v41
	v_cvt_pk_bf16_f32 v145, v42, v43
	v_cvt_pk_bf16_f32 v146, v36, v37
	v_cvt_pk_bf16_f32 v147, v38, v39
	global_store_dwordx4 v[140:141], v[144:147], off
.LBB0_763:
	v_mov_b32_e32 v149, v148
	s_nop 0
	s_waitcnt vmcnt(8)
	v_lshlrev_b32_e32 v144, 16, v154
	v_and_b32_e32 v145, 0xffff0000, v154
	v_lshlrev_b32_e32 v146, 16, v155
	v_and_b32_e32 v147, 0xffff0000, v155
	v_mov_b32_e32 v154, v148
	v_mov_b32_e32 v155, v148
	v_lshlrev_b32_e32 v150, 16, v152
	v_and_b32_e32 v151, 0xffff0000, v152
	v_lshlrev_b32_e32 v152, 16, v153
	v_and_b32_e32 v153, 0xffff0000, v153
	v_pk_mul_f32 v[10:11], v[10:11], v[154:155]
	v_pk_mul_f32 v[8:9], v[8:9], v[148:149]
	v_pk_mul_f32 v[6:7], v[6:7], v[154:155]
	v_pk_mul_f32 v[4:5], v[4:5], v[148:149]
	v_pk_fma_f32 v[10:11], v[138:139], v[10:11], v[152:153]
	v_pk_fma_f32 v[8:9], v[136:137], v[8:9], v[150:151]
	v_pk_fma_f32 v[6:7], v[134:135], v[6:7], v[146:147]
	v_pk_fma_f32 v[4:5], v[132:133], v[4:5], v[144:145]
	s_and_b64 vcc, exec, s[0:1]
	s_mov_b64 s[0:1], -1
	s_cbranch_vccnz .LBB0_772
	global_store_dwordx4 v[142:143], v[8:11], off offset:512
	global_store_dwordx4 v[142:143], v[4:7], off offset:528
	s_cbranch_execz .LBB0_773

.LBB0_773:
	v_cvt_pk_bf16_f32 v132, v8, v9
	v_cvt_pk_bf16_f32 v133, v10, v11
	v_cvt_pk_bf16_f32 v134, v4, v5
	v_cvt_pk_bf16_f32 v135, v6, v7
	global_store_dwordx4 v[140:141], v[132:135], off offset:256
	s_and_b64 vcc, exec, s[6:7]
	s_cbranch_vccz .LBB0_766

.LBB0_797:
	s_or_b64 exec, exec, s[2:3]
	s_waitcnt lgkmcnt(0)
	s_waitcnt lgkmcnt(0)
	s_barrier
	ds_read_b32 v0, v3
	v_add_u32_e32 v152, v2, v188
	v_ashrrev_i32_e32 v153, 31, v152
	v_lshl_add_u64 v[148:149], v[190:191], 1, s[22:23]
	v_lshlrev_b64 v[152:153], 11, v[152:153]
	v_lshl_add_u64 v[160:161], v[148:149], 0, v[152:153]
	s_waitcnt lgkmcnt(0)
	v_pk_mul_f32 v[152:153], v[130:131], v[0:1] op_sel_hi:[1,0]
	v_pk_mul_f32 v[154:155], v[128:129], v[0:1] op_sel_hi:[1,0]
	s_waitcnt vmcnt(0)
	v_pk_mul_f32 v[162:163], v[146:147], v[152:153]
	v_pk_mul_f32 v[152:153], v[144:145], v[154:155]
	v_pk_mul_f32 v[154:155], v[126:127], v[0:1] op_sel_hi:[1,0]
	v_pk_mul_f32 v[164:165], v[124:125], v[0:1] op_sel_hi:[1,0]
	v_pk_mul_f32 v[166:167], v[142:143], v[154:155]
	v_pk_mul_f32 v[154:155], v[140:141], v[164:165]
	v_cvt_pk_bf16_f32 v152, v152, v153
	v_cvt_pk_bf16_f32 v153, v162, v163
	v_pk_mul_f32 v[164:165], v[92:93], v[0:1] op_sel_hi:[1,0]
	v_cvt_pk_bf16_f32 v154, v154, v155
	v_cvt_pk_bf16_f32 v155, v166, v167
	global_store_dwordx4 v[160:161], v[152:155], off
	s_nop 1
	v_pk_mul_f32 v[152:153], v[98:99], v[0:1] op_sel_hi:[1,0]
	v_pk_mul_f32 v[154:155], v[96:97], v[0:1] op_sel_hi:[1,0]
	v_pk_mul_f32 v[162:163], v[138:139], v[152:153]
	v_pk_mul_f32 v[152:153], v[136:137], v[154:155]
	v_pk_mul_f32 v[154:155], v[94:95], v[0:1] op_sel_hi:[1,0]
	v_cvt_pk_bf16_f32 v152, v152, v153
	v_cvt_pk_bf16_f32 v153, v162, v163
	s_nop 0
	v_pk_mul_f32 v[166:167], v[134:135], v[154:155]
	v_pk_mul_f32 v[154:155], v[132:133], v[164:165]
	s_nop 0
	v_cvt_pk_bf16_f32 v154, v154, v155
	v_cvt_pk_bf16_f32 v155, v166, v167
	global_store_dwordx4 v[160:161], v[152:155], off offset:256
	ds_read_b32 v0, v3 offset:64
	s_waitcnt lgkmcnt(0)
	v_pk_mul_f32 v[164:165], v[116:117], v[0:1] op_sel_hi:[1,0]
	v_add_u32_e32 v152, v2, v189
	v_ashrrev_i32_e32 v153, 31, v152
	v_lshlrev_b64 v[152:153], 11, v[152:153]
	v_lshl_add_u64 v[160:161], v[148:149], 0, v[152:153]
	v_pk_mul_f32 v[152:153], v[122:123], v[0:1] op_sel_hi:[1,0]
	v_pk_mul_f32 v[154:155], v[120:121], v[0:1] op_sel_hi:[1,0]
	v_pk_mul_f32 v[162:163], v[146:147], v[152:153]
	v_pk_mul_f32 v[152:153], v[144:145], v[154:155]
	v_pk_mul_f32 v[154:155], v[118:119], v[0:1] op_sel_hi:[1,0]
	v_cvt_pk_bf16_f32 v152, v152, v153
	v_cvt_pk_bf16_f32 v153, v162, v163
	s_nop 0
	v_pk_mul_f32 v[166:167], v[142:143], v[154:155]
	v_pk_mul_f32 v[154:155], v[140:141], v[164:165]
	v_pk_mul_f32 v[164:165], v[84:85], v[0:1] op_sel_hi:[1,0]
	v_cvt_pk_bf16_f32 v154, v154, v155
	v_cvt_pk_bf16_f32 v155, v166, v167
	global_store_dwordx4 v[160:161], v[152:155], off
	s_nop 1
	v_pk_mul_f32 v[152:153], v[90:91], v[0:1] op_sel_hi:[1,0]
	v_pk_mul_f32 v[154:155], v[88:89], v[0:1] op_sel_hi:[1,0]
	v_pk_mul_f32 v[162:163], v[138:139], v[152:153]
	v_pk_mul_f32 v[152:153], v[136:137], v[154:155]
	v_pk_mul_f32 v[154:155], v[86:87], v[0:1] op_sel_hi:[1,0]
	v_cvt_pk_bf16_f32 v152, v152, v153
	v_cvt_pk_bf16_f32 v153, v162, v163
	s_nop 0
	v_pk_mul_f32 v[166:167], v[134:135], v[154:155]
	v_pk_mul_f32 v[154:155], v[132:133], v[164:165]
	s_nop 0
	v_cvt_pk_bf16_f32 v154, v154, v155
	v_cvt_pk_bf16_f32 v155, v166, v167
	global_store_dwordx4 v[160:161], v[152:155], off offset:256
	ds_read_b32 v0, v3 offset:128
	s_waitcnt lgkmcnt(0)
	v_pk_mul_f32 v[164:165], v[108:109], v[0:1] op_sel_hi:[1,0]
	v_add_u32_e32 v152, v2, v204
	v_ashrrev_i32_e32 v153, 31, v152
	v_lshlrev_b64 v[152:153], 11, v[152:153]
	v_lshl_add_u64 v[160:161], v[148:149], 0, v[152:153]
	v_pk_mul_f32 v[152:153], v[114:115], v[0:1] op_sel_hi:[1,0]
	v_pk_mul_f32 v[154:155], v[112:113], v[0:1] op_sel_hi:[1,0]
	v_pk_mul_f32 v[162:163], v[146:147], v[152:153]
	v_pk_mul_f32 v[152:153], v[144:145], v[154:155]
	v_pk_mul_f32 v[154:155], v[110:111], v[0:1] op_sel_hi:[1,0]
	v_cvt_pk_bf16_f32 v152, v152, v153
	v_cvt_pk_bf16_f32 v153, v162, v163
	s_nop 0
	v_pk_mul_f32 v[166:167], v[142:143], v[154:155]
	v_pk_mul_f32 v[154:155], v[140:141], v[164:165]
	v_pk_mul_f32 v[164:165], v[76:77], v[0:1] op_sel_hi:[1,0]
	v_cvt_pk_bf16_f32 v154, v154, v155
	v_cvt_pk_bf16_f32 v155, v166, v167
	global_store_dwordx4 v[160:161], v[152:155], off
	s_nop 1
	v_pk_mul_f32 v[152:153], v[82:83], v[0:1] op_sel_hi:[1,0]
	v_pk_mul_f32 v[154:155], v[80:81], v[0:1] op_sel_hi:[1,0]
	v_pk_mul_f32 v[162:163], v[138:139], v[152:153]
	v_pk_mul_f32 v[152:153], v[136:137], v[154:155]
	v_pk_mul_f32 v[154:155], v[78:79], v[0:1] op_sel_hi:[1,0]
	v_cvt_pk_bf16_f32 v152, v152, v153
	v_cvt_pk_bf16_f32 v153, v162, v163
	s_nop 0
	v_pk_mul_f32 v[166:167], v[134:135], v[154:155]
	v_pk_mul_f32 v[154:155], v[132:133], v[164:165]
	s_nop 0
	v_cvt_pk_bf16_f32 v154, v154, v155
	v_cvt_pk_bf16_f32 v155, v166, v167
	global_store_dwordx4 v[160:161], v[152:155], off offset:256
	ds_read_b32 v0, v3 offset:192
	s_waitcnt lgkmcnt(0)
	v_pk_mul_f32 v[164:165], v[100:101], v[0:1] op_sel_hi:[1,0]
	v_add_u32_e32 v152, v2, v196
	v_ashrrev_i32_e32 v153, 31, v152
	v_lshlrev_b64 v[152:153], 11, v[152:153]
	v_lshl_add_u64 v[160:161], v[148:149], 0, v[152:153]
	v_pk_mul_f32 v[152:153], v[106:107], v[0:1] op_sel_hi:[1,0]
	v_pk_mul_f32 v[154:155], v[104:105], v[0:1] op_sel_hi:[1,0]
	v_pk_mul_f32 v[162:163], v[146:147], v[152:153]
	v_pk_mul_f32 v[152:153], v[144:145], v[154:155]
	v_pk_mul_f32 v[154:155], v[102:103], v[0:1] op_sel_hi:[1,0]
	v_cvt_pk_bf16_f32 v152, v152, v153
	v_cvt_pk_bf16_f32 v153, v162, v163
	s_nop 0
	v_pk_mul_f32 v[166:167], v[142:143], v[154:155]
	v_pk_mul_f32 v[154:155], v[140:141], v[164:165]
	v_pk_mul_f32 v[164:165], v[68:69], v[0:1] op_sel_hi:[1,0]
	v_cvt_pk_bf16_f32 v154, v154, v155
	v_cvt_pk_bf16_f32 v155, v166, v167
	global_store_dwordx4 v[160:161], v[152:155], off
	s_nop 1
	v_pk_mul_f32 v[152:153], v[74:75], v[0:1] op_sel_hi:[1,0]
	v_pk_mul_f32 v[154:155], v[72:73], v[0:1] op_sel_hi:[1,0]
	v_pk_mul_f32 v[162:163], v[138:139], v[152:153]
	v_pk_mul_f32 v[152:153], v[136:137], v[154:155]
	v_pk_mul_f32 v[154:155], v[70:71], v[0:1] op_sel_hi:[1,0]
	v_cvt_pk_bf16_f32 v152, v152, v153
	v_cvt_pk_bf16_f32 v153, v162, v163
	s_nop 0
	v_pk_mul_f32 v[166:167], v[134:135], v[154:155]
	v_pk_mul_f32 v[154:155], v[132:133], v[164:165]
	s_nop 0
	v_cvt_pk_bf16_f32 v154, v154, v155
	v_cvt_pk_bf16_f32 v155, v166, v167
	global_store_dwordx4 v[160:161], v[152:155], off offset:256
	ds_read_b32 v0, v3 offset:512
	s_waitcnt lgkmcnt(0)
	v_pk_mul_f32 v[164:165], v[60:61], v[0:1] op_sel_hi:[1,0]
	v_add_u32_e32 v152, v2, v158
	v_ashrrev_i32_e32 v153, 31, v152
	v_lshlrev_b64 v[152:153], 11, v[152:153]
	v_lshl_add_u64 v[160:161], v[148:149], 0, v[152:153]
	v_pk_mul_f32 v[152:153], v[66:67], v[0:1] op_sel_hi:[1,0]
	v_pk_mul_f32 v[154:155], v[64:65], v[0:1] op_sel_hi:[1,0]
	v_pk_mul_f32 v[162:163], v[146:147], v[152:153]
	v_pk_mul_f32 v[152:153], v[144:145], v[154:155]
	v_pk_mul_f32 v[154:155], v[62:63], v[0:1] op_sel_hi:[1,0]
	v_cvt_pk_bf16_f32 v152, v152, v153
	v_cvt_pk_bf16_f32 v153, v162, v163
	s_nop 0
	v_pk_mul_f32 v[166:167], v[142:143], v[154:155]
	v_pk_mul_f32 v[154:155], v[140:141], v[164:165]
	v_pk_mul_f32 v[164:165], v[28:29], v[0:1] op_sel_hi:[1,0]
	v_cvt_pk_bf16_f32 v154, v154, v155
	v_cvt_pk_bf16_f32 v155, v166, v167
	global_store_dwordx4 v[160:161], v[152:155], off
	s_nop 1
	v_pk_mul_f32 v[152:153], v[34:35], v[0:1] op_sel_hi:[1,0]
	v_pk_mul_f32 v[154:155], v[32:33], v[0:1] op_sel_hi:[1,0]
	v_pk_mul_f32 v[162:163], v[138:139], v[152:153]
	v_pk_mul_f32 v[152:153], v[136:137], v[154:155]
	v_pk_mul_f32 v[154:155], v[30:31], v[0:1] op_sel_hi:[1,0]
	v_cvt_pk_bf16_f32 v152, v152, v153
	v_cvt_pk_bf16_f32 v153, v162, v163
	s_nop 0
	v_pk_mul_f32 v[166:167], v[134:135], v[154:155]
	v_pk_mul_f32 v[154:155], v[132:133], v[164:165]
	s_nop 0
	v_cvt_pk_bf16_f32 v154, v154, v155
	v_cvt_pk_bf16_f32 v155, v166, v167
	global_store_dwordx4 v[160:161], v[152:155], off offset:256
	ds_read_b32 v0, v3 offset:576
	s_waitcnt lgkmcnt(0)
	v_pk_mul_f32 v[162:163], v[52:53], v[0:1] op_sel_hi:[1,0]
	v_add_u32_e32 v152, v2, v159
	v_ashrrev_i32_e32 v153, 31, v152
	v_lshlrev_b64 v[152:153], 11, v[152:153]
	v_lshl_add_u64 v[158:159], v[148:149], 0, v[152:153]
	v_pk_mul_f32 v[152:153], v[58:59], v[0:1] op_sel_hi:[1,0]
	v_pk_mul_f32 v[154:155], v[56:57], v[0:1] op_sel_hi:[1,0]
	v_pk_mul_f32 v[160:161], v[146:147], v[152:153]
	v_pk_mul_f32 v[152:153], v[144:145], v[154:155]
	v_pk_mul_f32 v[154:155], v[54:55], v[0:1] op_sel_hi:[1,0]
	v_cvt_pk_bf16_f32 v152, v152, v153
	v_cvt_pk_bf16_f32 v153, v160, v161
	s_nop 0
	v_pk_mul_f32 v[164:165], v[142:143], v[154:155]
	v_pk_mul_f32 v[154:155], v[140:141], v[162:163]
	v_pk_mul_f32 v[162:163], v[20:21], v[0:1] op_sel_hi:[1,0]
	v_cvt_pk_bf16_f32 v154, v154, v155
	v_cvt_pk_bf16_f32 v155, v164, v165
	global_store_dwordx4 v[158:159], v[152:155], off
	s_nop 1
	v_pk_mul_f32 v[152:153], v[26:27], v[0:1] op_sel_hi:[1,0]
	v_pk_mul_f32 v[154:155], v[24:25], v[0:1] op_sel_hi:[1,0]
	v_pk_mul_f32 v[160:161], v[138:139], v[152:153]
	v_pk_mul_f32 v[152:153], v[136:137], v[154:155]
	v_pk_mul_f32 v[154:155], v[22:23], v[0:1] op_sel_hi:[1,0]
	v_cvt_pk_bf16_f32 v152, v152, v153
	v_cvt_pk_bf16_f32 v153, v160, v161
	s_nop 0
	v_pk_mul_f32 v[164:165], v[134:135], v[154:155]
	v_pk_mul_f32 v[154:155], v[132:133], v[162:163]
	s_nop 0
	v_cvt_pk_bf16_f32 v154, v154, v155
	v_cvt_pk_bf16_f32 v155, v164, v165
	global_store_dwordx4 v[158:159], v[152:155], off offset:256
	ds_read_b32 v0, v3 offset:640
	s_waitcnt lgkmcnt(0)
	v_pk_mul_f32 v[160:161], v[44:45], v[0:1] op_sel_hi:[1,0]
	v_add_u32_e32 v152, v2, v156
	v_ashrrev_i32_e32 v153, 31, v152
	v_lshlrev_b64 v[152:153], 11, v[152:153]
	v_lshl_add_u64 v[156:157], v[148:149], 0, v[152:153]
	v_pk_mul_f32 v[152:153], v[50:51], v[0:1] op_sel_hi:[1,0]
	v_pk_mul_f32 v[154:155], v[48:49], v[0:1] op_sel_hi:[1,0]
	v_pk_mul_f32 v[158:159], v[146:147], v[152:153]
	v_pk_mul_f32 v[152:153], v[144:145], v[154:155]
	v_pk_mul_f32 v[154:155], v[46:47], v[0:1] op_sel_hi:[1,0]
	v_cvt_pk_bf16_f32 v152, v152, v153
	v_cvt_pk_bf16_f32 v153, v158, v159
	v_add_u32_e32 v2, v2, v150
	v_pk_mul_f32 v[162:163], v[142:143], v[154:155]
	v_pk_mul_f32 v[154:155], v[140:141], v[160:161]
	v_pk_mul_f32 v[160:161], v[12:13], v[0:1] op_sel_hi:[1,0]
	v_cvt_pk_bf16_f32 v154, v154, v155
	v_cvt_pk_bf16_f32 v155, v162, v163
	global_store_dwordx4 v[156:157], v[152:155], off
	s_nop 1
	v_pk_mul_f32 v[152:153], v[18:19], v[0:1] op_sel_hi:[1,0]
	v_pk_mul_f32 v[154:155], v[16:17], v[0:1] op_sel_hi:[1,0]
	v_pk_mul_f32 v[158:159], v[138:139], v[152:153]
	v_pk_mul_f32 v[152:153], v[136:137], v[154:155]
	v_pk_mul_f32 v[154:155], v[14:15], v[0:1] op_sel_hi:[1,0]
	v_cvt_pk_bf16_f32 v152, v152, v153
	v_cvt_pk_bf16_f32 v153, v158, v159
	s_nop 0
	v_pk_mul_f32 v[162:163], v[134:135], v[154:155]
	v_pk_mul_f32 v[154:155], v[132:133], v[160:161]
	s_nop 0
	v_cvt_pk_bf16_f32 v154, v154, v155
	v_cvt_pk_bf16_f32 v155, v162, v163
	global_store_dwordx4 v[156:157], v[152:155], off offset:256
	ds_read_b32 v0, v3 offset:704
	v_ashrrev_i32_e32 v3, 31, v2
	v_lshlrev_b64 v[2:3], 11, v[2:3]
	v_lshl_add_u64 v[2:3], v[148:149], 0, v[2:3]
	s_waitcnt lgkmcnt(0)
	v_pk_mul_f32 v[148:149], v[42:43], v[0:1] op_sel_hi:[1,0]
	v_pk_mul_f32 v[150:151], v[40:41], v[0:1] op_sel_hi:[1,0]
	v_pk_mul_f32 v[146:147], v[146:147], v[148:149]
	v_pk_mul_f32 v[144:145], v[144:145], v[150:151]
	v_pk_mul_f32 v[148:149], v[38:39], v[0:1] op_sel_hi:[1,0]
	v_pk_mul_f32 v[150:151], v[36:37], v[0:1] op_sel_hi:[1,0]
	v_pk_mul_f32 v[148:149], v[142:143], v[148:149]
	v_pk_mul_f32 v[142:143], v[140:141], v[150:151]
	v_cvt_pk_bf16_f32 v140, v144, v145
	v_cvt_pk_bf16_f32 v141, v146, v147
	s_nop 0
	v_cvt_pk_bf16_f32 v142, v142, v143
	v_cvt_pk_bf16_f32 v143, v148, v149
	global_store_dwordx4 v[2:3], v[140:143], off
	s_nop 1
	v_pk_mul_f32 v[140:141], v[10:11], v[0:1] op_sel_hi:[1,0]
	v_pk_mul_f32 v[142:143], v[8:9], v[0:1] op_sel_hi:[1,0]
	v_pk_mul_f32 v[138:139], v[138:139], v[140:141]
	v_pk_mul_f32 v[136:137], v[136:137], v[142:143]
	v_pk_mul_f32 v[140:141], v[6:7], v[0:1] op_sel_hi:[1,0]
	v_pk_mul_f32 v[142:143], v[4:5], v[0:1] op_sel_hi:[1,0]
	v_pk_mul_f32 v[140:141], v[134:135], v[140:141]
	v_pk_mul_f32 v[134:135], v[132:133], v[142:143]
	v_cvt_pk_bf16_f32 v132, v136, v137
	v_cvt_pk_bf16_f32 v133, v138, v139
	s_nop 0
	v_cvt_pk_bf16_f32 v134, v134, v135
	v_cvt_pk_bf16_f32 v135, v140, v141
	global_store_dwordx4 v[2:3], v[132:135], off offset:256
	s_andn2_b64 vcc, exec, s[72:73]
	s_movk_i32 s73, 0x110
	s_cbranch_vccnz .LBB0_516
